# attention: second softmax half interleaved with first eight PV MFMAs; scan normalised state
# speedup vs baseline: 1.0155x; 1.0073x over previous
; __device__ __forceinline__ void partialSM(f32x16& p0, f32x16& p1, float& m_reg, float& mn, float& alpha) {
;     constexpr float C = SCALE * 1.4426950408889634f;
;     float pmax = p0[0];
; #pragma unroll
;     for (int r = 1; r < 16; ++r) pmax = fmaxf(pmax, p0[r]);
; #pragma unroll
;     for (int r = 0; r < 16; ++r) pmax = fmaxf(pmax, p1[r]);
;     { auto rr = __builtin_amdgcn_permlane32_swap(__float_as_uint(pmax), __float_as_uint(pmax), false, false);
;       pmax = fmaxf(__uint_as_float(rr[0]), __uint_as_float(rr[1])); }
;     if (__builtin_expect(__all(pmax - m_reg <= THR / SCALE), 1)) { mn = m_reg; alpha = 1.f; }
;     else { mn = fmaxf(m_reg, pmax); alpha = __builtin_amdgcn_exp2f((m_reg - mn) * C); m_reg = mn; }
;     const float mnC = -mn * C;
; #pragma unroll
;     for (int r = 0; r < 16; ++r) p0[r] = __builtin_amdgcn_exp2f(fmaf(p0[r], C, mnC));
; #pragma unroll
;     for (int r = 0; r < 16; ++r) p1[r] = __builtin_amdgcn_exp2f(fmaf(p1[r], C, mnC));
; }
; __device__ __forceinline__ void finishSM(f32x16& p0, f32x16& p1, float alpha, float& l_reg, bf16x8& pa0, bf16x8& pa1, bf16x8& pa2, bf16x8& pa3) {
;     float ps = 0;
; #pragma unroll
;     for (int r = 0; r < 16; ++r) ps += p0[r];
; #pragma unroll
;     for (int r = 0; r < 16; ++r) ps += p1[r];
;     { auto rr = __builtin_amdgcn_permlane32_swap(__float_as_uint(ps), __float_as_uint(ps), false, false);
;       ps = __uint_as_float(rr[0]) + __uint_as_float(rr[1]); }
;     l_reg = l_reg * alpha + ps;
;     ...
;     PK4(p0, 0, pa0); PK4(p0, 8, pa1); PK4(p1, 0, pa2); PK4(p1, 8, pa3);
;     ...
; }
; __device__ __forceinline__ void qkt(f32x16& p0, f32x16& p1, const char* Kn, const char* Kr, const bf16x8* qr, int r32, int hi) {
;     p0 = f32x16{}; p1 = f32x16{};
; #pragma unroll
;     for (int d0 = 0; d0 < 8; ++d0) { const int cb = (d0 * 16 + hi * 8) * 2;
;         const bf16x8 b0 = *reinterpret_cast<const bf16x8*>(Kn + KSWZ(r32, cb));
;         const bf16x8 b1 = *reinterpret_cast<const bf16x8*>(Kn + KSWZ(32 + r32, cb));
;         p0 = __builtin_amdgcn_mfma_f32_32x32x16_bf16(b0, qr[d0], p0, 0, 0, 0);
;         p1 = __builtin_amdgcn_mfma_f32_32x32x16_bf16(b1, qr[d0], p1, 0, 0, 0); }
; #pragma unroll
;     for (int d0 = 0; d0 < 4; ++d0) { const int cb = (d0 * 16 + hi * 8) * 2;
;         const bf16x8 b0 = *reinterpret_cast<const bf16x8*>(Kr + KSWZ(r32, cb));
.LBB0_60:
	s_and_b32 s16, s23, 0x4000
	s_add_i32 s2, s16, 0
	s_add_i32 s3, s2, 0x10000
	v_add_u32_e32 v0, s2, v221
	ds_read_b128 v[66:69], v0 offset:32768
	ds_read_b128 v[70:73], v0 offset:40960
	v_add_u32_e32 v0, s2, v222
	ds_read_b128 v[232:235], v0 offset:32768
	ds_read_b128 v[236:239], v0 offset:40960
	v_add_u32_e32 v0, s2, v223
	ds_read_b128 v[240:243], v0 offset:32768
	ds_read_b128 v[244:247], v0 offset:40960
	v_add_u32_e32 v0, s2, v224
	ds_read_b128 v[206:209], v0 offset:32768
	ds_read_b128 v[210:213], v0 offset:40960
	s_waitcnt lgkmcnt(7)
	v_mfma_f32_32x32x16_bf16 v[82:97], v[66:69], v[98:101], 0
	s_waitcnt lgkmcnt(6)
	v_mfma_f32_32x32x16_bf16 v[66:81], v[70:73], v[98:101], 0
	s_waitcnt lgkmcnt(5)
	v_mfma_f32_32x32x16_bf16 v[82:97], v[232:235], v[102:105], v[82:97]
	s_waitcnt lgkmcnt(4)
	v_mfma_f32_32x32x16_bf16 v[66:81], v[236:239], v[102:105], v[66:81]
	v_add3_u32 v0, s2, v225, v220
	ds_read_b128 v[232:235], v0 offset:32768
	ds_read_b128 v[236:239], v0 offset:40960
	s_waitcnt lgkmcnt(5)
	v_mfma_f32_32x32x16_bf16 v[82:97], v[240:243], v[106:109], v[82:97]
	s_waitcnt lgkmcnt(4)
	v_mfma_f32_32x32x16_bf16 v[66:81], v[244:247], v[106:109], v[66:81]
	v_add3_u32 v0, s2, v226, v220
	ds_read_b128 v[240:243], v0 offset:32768
	ds_read_b128 v[244:247], v0 offset:40960
	s_waitcnt lgkmcnt(5)
	v_mfma_f32_32x32x16_bf16 v[82:97], v[206:209], v[110:113], v[82:97]
	s_waitcnt lgkmcnt(4)
	v_mfma_f32_32x32x16_bf16 v[66:81], v[210:213], v[110:113], v[66:81]
	v_add3_u32 v0, s2, v227, v220
	ds_read_b128 v[206:209], v0 offset:32768
	ds_read_b128 v[210:213], v0 offset:40960
	s_waitcnt lgkmcnt(5)
	v_mfma_f32_32x32x16_bf16 v[82:97], v[232:235], v[114:117], v[82:97]
	s_waitcnt lgkmcnt(4)
	v_mfma_f32_32x32x16_bf16 v[66:81], v[236:239], v[114:117], v[66:81]
	v_add3_u32 v0, s2, v228, v220
	ds_read_b128 v[232:235], v0 offset:32768
	ds_read_b128 v[236:239], v0 offset:40960
	s_waitcnt lgkmcnt(5)
	v_mfma_f32_32x32x16_bf16 v[82:97], v[240:243], v[118:121], v[82:97]
	s_waitcnt lgkmcnt(4)
	v_mfma_f32_32x32x16_bf16 v[66:81], v[244:247], v[118:121], v[66:81]
	v_add_u32_e32 v0, s3, v221
	ds_read_b128 v[240:243], v0 offset:0
	ds_read_b128 v[244:247], v0 offset:8192
	s_waitcnt lgkmcnt(5)
	v_mfma_f32_32x32x16_bf16 v[82:97], v[206:209], v[122:125], v[82:97]
	s_waitcnt lgkmcnt(4)
	v_mfma_f32_32x32x16_bf16 v[66:81], v[210:213], v[122:125], v[66:81]
	v_add_u32_e32 v0, s3, v222
	ds_read_b128 v[206:209], v0 offset:0
	ds_read_b128 v[210:213], v0 offset:8192
	s_waitcnt lgkmcnt(5)
	v_mfma_f32_32x32x16_bf16 v[82:97], v[232:235], v[126:129], v[82:97]
	s_waitcnt lgkmcnt(4)
	v_mfma_f32_32x32x16_bf16 v[66:81], v[236:239], v[126:129], v[66:81]
	v_add_u32_e32 v0, s3, v223
	ds_read_b128 v[232:235], v0 offset:0
	ds_read_b128 v[236:239], v0 offset:8192
	s_waitcnt lgkmcnt(5)
	v_mfma_f32_32x32x16_bf16 v[82:97], v[240:243], v[130:133], v[82:97]
	s_waitcnt lgkmcnt(4)
	v_mfma_f32_32x32x16_bf16 v[66:81], v[244:247], v[130:133], v[66:81]
	v_add_u32_e32 v0, s3, v224
	ds_read_b128 v[240:243], v0 offset:0
	ds_read_b128 v[244:247], v0 offset:8192
	s_waitcnt lgkmcnt(5)
	v_mfma_f32_32x32x16_bf16 v[82:97], v[206:209], v[134:137], v[82:97]
	s_waitcnt lgkmcnt(4)
	v_mfma_f32_32x32x16_bf16 v[66:81], v[210:213], v[134:137], v[66:81]
	s_waitcnt lgkmcnt(3)
	v_mfma_f32_32x32x16_bf16 v[82:97], v[232:235], v[138:141], v[82:97]
	s_waitcnt lgkmcnt(2)
	v_mfma_f32_32x32x16_bf16 v[66:81], v[236:239], v[138:141], v[66:81]
	s_waitcnt lgkmcnt(1)
	v_mfma_f32_32x32x16_bf16 v[82:97], v[240:243], v[142:145], v[82:97]
	s_waitcnt lgkmcnt(0)
	v_mfma_f32_32x32x16_bf16 v[66:81], v[244:247], v[142:145], v[66:81]
	s_mov_b32 s2, 0x42ddb3d8
	s_nop 9
	v_max_f32_e32 v0, v83, v83
	v_max_f32_e32 v202, v82, v82
	v_max_f32_e32 v0, v202, v0
	v_max3_f32 v0, v0, v84, v85
	v_max3_f32 v0, v0, v86, v87
	v_max3_f32 v0, v0, v88, v89
	v_max3_f32 v0, v0, v90, v91
	v_max3_f32 v0, v0, v92, v93
	v_max3_f32 v0, v0, v94, v95
	v_max3_f32 v0, v0, v96, v97
	v_max3_f32 v0, v0, v66, v67
	v_max3_f32 v0, v0, v68, v69
	v_max3_f32 v0, v0, v70, v71
	v_max3_f32 v0, v0, v72, v73
	v_max3_f32 v0, v0, v74, v75
	v_max3_f32 v0, v0, v76, v77
	v_max3_f32 v0, v0, v78, v79
	v_max3_f32 v0, v0, v80, v81
	v_mov_b32_e32 v202, v0
	s_nop 1
	v_permlane32_swap_b32_e32 v0, v202
	v_max_f32_e32 v202, v202, v202
	v_max_f32_e32 v0, v0, v0
	v_max_f32_e32 v0, v0, v202
	v_sub_f32_e32 v202, v0, v183
	v_cmp_ge_f32_e32 vcc, s2, v202
	s_cmp_eq_u64 vcc, exec
	v_max_f32_e32 v202, v183, v183
	s_cselect_b64 vcc, -1, 0
	v_max_f32_e32 v202, v202, v0
	v_sub_f32_e32 v0, v183, v202
	v_cndmask_b32_e32 v183, v202, v183, vcc
	v_mul_f32_e32 v202, 0xbdd53b94, v183
	v_fmamk_f32 v82, v82, 0x3dd53b94, v202
	v_fmamk_f32 v83, v83, 0x3dd53b94, v202
	v_fmamk_f32 v84, v84, 0x3dd53b94, v202
	v_fmamk_f32 v85, v85, 0x3dd53b94, v202
	v_fmamk_f32 v86, v86, 0x3dd53b94, v202
	v_fmamk_f32 v87, v87, 0x3dd53b94, v202
	v_fmamk_f32 v88, v88, 0x3dd53b94, v202
	v_fmamk_f32 v89, v89, 0x3dd53b94, v202
	v_exp_f32_e32 v82, v82
	v_exp_f32_e32 v83, v83
	v_exp_f32_e32 v84, v84
	v_exp_f32_e32 v85, v85
	v_exp_f32_e32 v86, v86
	v_exp_f32_e32 v87, v87
	v_exp_f32_e32 v88, v88
	v_exp_f32_e32 v89, v89
	v_fmamk_f32 v90, v90, 0x3dd53b94, v202
	v_fmamk_f32 v91, v91, 0x3dd53b94, v202
	v_fmamk_f32 v92, v92, 0x3dd53b94, v202
	v_fmamk_f32 v93, v93, 0x3dd53b94, v202
	v_fmamk_f32 v94, v94, 0x3dd53b94, v202
	v_fmamk_f32 v95, v95, 0x3dd53b94, v202
	v_fmamk_f32 v96, v96, 0x3dd53b94, v202
	v_fmamk_f32 v97, v97, 0x3dd53b94, v202
	v_mul_f32_e32 v0, 0x3dd53b94, v0
	v_exp_f32_e32 v90, v90
	v_add_f32_e32 v240, v82, v83
	v_exp_f32_e32 v91, v91
	v_add_f32_e32 v241, v84, v85
	v_exp_f32_e32 v92, v92
	v_add_f32_e32 v240, v86, v240
	v_exp_f32_e32 v93, v93
	v_add_f32_e32 v241, v87, v241
	v_exp_f32_e32 v94, v94
	v_add_f32_e32 v240, v88, v240
	v_exp_f32_e32 v95, v95
	v_add_f32_e32 v241, v89, v241
	v_exp_f32_e32 v96, v96
	v_exp_f32_e32 v97, v97
	v_exp_f32_e32 v0, v0
	v_add_f32_e32 v240, v90, v240
	v_add_f32_e32 v241, v91, v241
	v_add_f32_e32 v240, v92, v240
	v_add_f32_e32 v241, v93, v241
	v_add_f32_e32 v240, v94, v240
	v_add_f32_e32 v241, v95, v241
	v_add_f32_e32 v240, v96, v240
	v_add_f32_e32 v241, v97, v241
	v_cndmask_b32_e64 v0, v0, 1.0, vcc
	v_cvt_pk_bf16_f32 v244, v82, v83
	v_cvt_pk_bf16_f32 v245, v84, v85
	v_cvt_pk_bf16_f32 v246, v86, v87
	v_cvt_pk_bf16_f32 v247, v88, v89
	v_cvt_pk_bf16_f32 v248, v90, v91
	v_cvt_pk_bf16_f32 v249, v92, v93
	v_cvt_pk_bf16_f32 v250, v94, v95
	v_cvt_pk_bf16_f32 v251, v96, v97
	s_nop 1
	v_permlane32_swap_b32_e32 v244, v246
	v_permlane32_swap_b32_e32 v245, v247
	v_permlane32_swap_b32_e32 v248, v250
	v_permlane32_swap_b32_e32 v249, v251
	v_cmp_gt_f32_e32 vcc, 1.0, v0
	s_cbranch_vccz .LBB0_64
	s_and_saveexec_b64 s[2:3], s[6:7]
	ds_write_b32 v229, v0 offset:128
	s_or_b64 exec, exec, s[2:3]
	s_waitcnt lgkmcnt(0)
	v_add_u32_e32 v96, v167, v219
	ds_read_b128 v[84:87], v96 offset:224
	ds_read_b128 v[88:91], v96 offset:192
	ds_read_b128 v[92:95], v96 offset:160
	ds_read_b128 v[232:235], v96 offset:128
	s_waitcnt lgkmcnt(3)
	v_pk_mul_f32 v[62:63], v[62:63], v[84:85]
	s_waitcnt lgkmcnt(2)
	v_pk_mul_f32 v[58:59], v[58:59], v[88:89]
	s_waitcnt lgkmcnt(1)
	v_pk_mul_f32 v[54:55], v[54:55], v[92:93]
	v_pk_mul_f32 v[64:65], v[64:65], v[86:87]
	v_pk_mul_f32 v[60:61], v[60:61], v[90:91]
	v_pk_mul_f32 v[56:57], v[56:57], v[94:95]
	s_waitcnt lgkmcnt(0)
	v_pk_mul_f32 v[52:53], v[52:53], v[234:235]
	v_pk_mul_f32 v[50:51], v[50:51], v[232:233]
	v_pk_mul_f32 v[46:47], v[46:47], v[84:85]
	v_pk_mul_f32 v[42:43], v[42:43], v[88:89]
	v_pk_mul_f32 v[38:39], v[38:39], v[92:93]
	v_pk_mul_f32 v[48:49], v[48:49], v[86:87]
	v_pk_mul_f32 v[44:45], v[44:45], v[90:91]
	v_pk_mul_f32 v[40:41], v[40:41], v[94:95]
	v_pk_mul_f32 v[36:37], v[36:37], v[234:235]
	v_pk_mul_f32 v[34:35], v[34:35], v[232:233]
	v_pk_mul_f32 v[30:31], v[30:31], v[84:85]
	v_pk_mul_f32 v[26:27], v[26:27], v[88:89]
	v_pk_mul_f32 v[22:23], v[22:23], v[92:93]
	v_pk_mul_f32 v[32:33], v[32:33], v[86:87]
	v_pk_mul_f32 v[28:29], v[28:29], v[90:91]
	v_pk_mul_f32 v[24:25], v[24:25], v[94:95]
	v_pk_mul_f32 v[20:21], v[20:21], v[234:235]
	v_pk_mul_f32 v[18:19], v[18:19], v[232:233]
	v_pk_mul_f32 v[14:15], v[14:15], v[84:85]
	v_pk_mul_f32 v[10:11], v[10:11], v[88:89]
	v_pk_mul_f32 v[6:7], v[6:7], v[92:93]
	v_pk_mul_f32 v[16:17], v[16:17], v[86:87]
	v_pk_mul_f32 v[12:13], v[12:13], v[90:91]
	v_pk_mul_f32 v[8:9], v[8:9], v[94:95]
	v_pk_mul_f32 v[4:5], v[4:5], v[234:235]
	v_pk_mul_f32 v[2:3], v[2:3], v[232:233]
; __device__ __forceinline__ void finishSM(f32x16& p0, f32x16& p1, float alpha, float& l_reg, bf16x8& pa0, bf16x8& pa1, bf16x8& pa2, bf16x8& pa3) {
;     float ps = 0;
; #pragma unroll
;     for (int r = 0; r < 16; ++r) ps += p0[r];
; #pragma unroll
;     for (int r = 0; r < 16; ++r) ps += p1[r];
;     { auto rr = __builtin_amdgcn_permlane32_swap(__float_as_uint(ps), __float_as_uint(ps), false, false);
;       ps = __uint_as_float(rr[0]) + __uint_as_float(rr[1]); }
;     l_reg = l_reg * alpha + ps;
;     ...
;     PK4(p0, 0, pa0); PK4(p0, 8, pa1); PK4(p1, 0, pa2); PK4(p1, 8, pa3);
;     ...
; }
; __device__ __forceinline__ void qkt(f32x16& p0, f32x16& p1, const char* Kn, const char* Kr, const bf16x8* qr, int r32, int hi) {
;     p0 = f32x16{}; p1 = f32x16{};
; #pragma unroll
;     for (int d0 = 0; d0 < 8; ++d0) { const int cb = (d0 * 16 + hi * 8) * 2;
;         const bf16x8 b0 = *reinterpret_cast<const bf16x8*>(Kn + KSWZ(r32, cb));
;         const bf16x8 b1 = *reinterpret_cast<const bf16x8*>(Kn + KSWZ(32 + r32, cb));
;         p0 = __builtin_amdgcn_mfma_f32_32x32x16_bf16(b0, qr[d0], p0, 0, 0, 0);
;         p1 = __builtin_amdgcn_mfma_f32_32x32x16_bf16(b1, qr[d0], p1, 0, 0, 0); }
; #pragma unroll
;     for (int d0 = 0; d0 < 4; ++d0) { const int cb = (d0 * 16 + hi * 8) * 2;
;         const bf16x8 b0 = *reinterpret_cast<const bf16x8*>(Kr + KSWZ(r32, cb));
;         const bf16x8 b1 = *reinterpret_cast<const bf16x8*>(Kr + KSWZ(32 + r32, cb));
;         p0 = __builtin_amdgcn_mfma_f32_32x32x16_bf16(b0, qr[8 + d0], p0, 0, 0, 0);
;         p1 = __builtin_amdgcn_mfma_f32_32x32x16_bf16(b1, qr[8 + d0], p1, 0, 0, 0); }
; }
; __device__ __forceinline__ int v_st(int k, int c) { const int kk = (k & ~0xC) | ((k & 4) << 1) | ((k & 8) >> 1); return ((kk >> 3) * 4 + (c >> 5)) * 512 + ((kk & 7) * 32 + (c & 31)) * 2; }
; __device__ __forceinline__ int v_rd_base(int lane) { return ((lane & 3) << 3) | (((lane >> 2) & 3) << 6) | (((lane >> 4) & 1) << 5) | (((lane >> 5) & 1) << 8); }
; template <int OFF> __device__ __forceinline__ s16x4 tr_read(int vb) {
;     s16x4 r; asm volatile("ds_read_b64_tr_b16 %0, %1 offset:%2" : "=&v"(r) : "v"(vb), "i"(OFF) : "memory"); return r;
; }
; template <int D0> __device__ __forceinline__ void pv_one(f32x16& od, int vb, bf16x8 pa0, bf16x8 pa1, bf16x8 pa2, bf16x8 pa3) {
.LBB0_64:
	v_add_u32_e32 v96, s16, v230
	ds_read_b64_tr_b16 v[84:85], v96 offset:0x0
	ds_read_b64_tr_b16 v[86:87], v96 offset:0x800
	ds_read_b64_tr_b16 v[88:89], v96 offset:0x1000
	ds_read_b64_tr_b16 v[90:91], v96 offset:0x1800
	ds_read_b64_tr_b16 v[92:93], v96 offset:0x200
	ds_read_b64_tr_b16 v[94:95], v96 offset:0xa00
	ds_read_b64_tr_b16 v[232:233], v96 offset:0x1200
	ds_read_b64_tr_b16 v[234:235], v96 offset:0x1a00
	s_waitcnt lgkmcnt(6)
	v_mfma_f32_32x32x16_bf16 v[50:65], v[244:247], v[84:87], v[50:65]
	ds_read_b64_tr_b16 v[84:85], v96 offset:0x400
	ds_read_b64_tr_b16 v[86:87], v96 offset:0xc00
	v_fmamk_f32 v66, v66, 0x3dd53b94, v202
	v_fmamk_f32 v67, v67, 0x3dd53b94, v202
	v_fmamk_f32 v68, v68, 0x3dd53b94, v202
	v_fmamk_f32 v69, v69, 0x3dd53b94, v202
	v_fmamk_f32 v70, v70, 0x3dd53b94, v202
	v_fmamk_f32 v71, v71, 0x3dd53b94, v202
	v_fmamk_f32 v72, v72, 0x3dd53b94, v202
	v_fmamk_f32 v73, v73, 0x3dd53b94, v202
	s_waitcnt lgkmcnt(6)
	v_mfma_f32_32x32x16_bf16 v[50:65], v[248:251], v[88:91], v[50:65]
	ds_read_b64_tr_b16 v[88:89], v96 offset:0x1400
	ds_read_b64_tr_b16 v[90:91], v96 offset:0x1c00
	v_exp_f32_e32 v66, v66
	v_exp_f32_e32 v67, v67
	v_exp_f32_e32 v68, v68
	v_exp_f32_e32 v69, v69
	v_exp_f32_e32 v70, v70
	v_exp_f32_e32 v71, v71
	v_exp_f32_e32 v72, v72
	v_exp_f32_e32 v73, v73
	s_waitcnt lgkmcnt(6)
	v_mfma_f32_32x32x16_bf16 v[34:49], v[244:247], v[92:95], v[34:49]
	ds_read_b64_tr_b16 v[92:93], v96 offset:0x600
	ds_read_b64_tr_b16 v[94:95], v96 offset:0xe00
	v_fmamk_f32 v74, v74, 0x3dd53b94, v202
	v_fmamk_f32 v75, v75, 0x3dd53b94, v202
	v_fmamk_f32 v76, v76, 0x3dd53b94, v202
	v_fmamk_f32 v77, v77, 0x3dd53b94, v202
	v_fmamk_f32 v78, v78, 0x3dd53b94, v202
	v_fmamk_f32 v79, v79, 0x3dd53b94, v202
	v_fmamk_f32 v80, v80, 0x3dd53b94, v202
	v_fmamk_f32 v81, v81, 0x3dd53b94, v202
	s_waitcnt lgkmcnt(6)
	v_mfma_f32_32x32x16_bf16 v[34:49], v[248:251], v[232:235], v[34:49]
	ds_read_b64_tr_b16 v[232:233], v96 offset:0x1600
	ds_read_b64_tr_b16 v[234:235], v96 offset:0x1e00
	v_exp_f32_e32 v74, v74
	v_add_f32_e32 v242, v66, v67
	v_exp_f32_e32 v75, v75
	v_add_f32_e32 v243, v68, v69
	v_exp_f32_e32 v76, v76
	v_add_f32_e32 v242, v70, v242
	v_exp_f32_e32 v77, v77
	v_add_f32_e32 v243, v71, v243
	s_waitcnt lgkmcnt(6)
	v_mfma_f32_32x32x16_bf16 v[18:33], v[244:247], v[84:87], v[18:33]
	ds_read_b64_tr_b16 v[84:85], v96 offset:0x2000
	ds_read_b64_tr_b16 v[86:87], v96 offset:0x2800
	v_exp_f32_e32 v78, v78
	v_add_f32_e32 v242, v72, v242
	v_exp_f32_e32 v79, v79
	v_add_f32_e32 v243, v73, v243
	v_exp_f32_e32 v80, v80
	v_exp_f32_e32 v81, v81
	v_add_f32_e32 v242, v74, v242
	v_add_f32_e32 v243, v75, v243
	s_waitcnt lgkmcnt(6)
	v_mfma_f32_32x32x16_bf16 v[18:33], v[248:251], v[88:91], v[18:33]
	ds_read_b64_tr_b16 v[88:89], v96 offset:0x3000
	ds_read_b64_tr_b16 v[90:91], v96 offset:0x3800
	v_add_f32_e32 v242, v76, v242
	v_add_f32_e32 v243, v77, v243
	v_add_f32_e32 v242, v78, v242
	v_add_f32_e32 v243, v79, v243
	v_add_f32_e32 v242, v80, v242
	v_add_f32_e32 v243, v81, v243
	v_add_f32_e32 v240, v240, v241
	v_add_f32_e32 v242, v242, v243
	s_waitcnt lgkmcnt(6)
	v_mfma_f32_32x32x16_bf16 v[2:17], v[244:247], v[92:95], v[2:17]
	ds_read_b64_tr_b16 v[92:93], v96 offset:0x2200
	ds_read_b64_tr_b16 v[94:95], v96 offset:0x2a00
	v_cvt_pk_bf16_f32 v66, v66, v67
	v_cvt_pk_bf16_f32 v67, v68, v69
	v_cvt_pk_bf16_f32 v68, v70, v71
	v_cvt_pk_bf16_f32 v69, v72, v73
	v_cvt_pk_bf16_f32 v70, v74, v75
	v_cvt_pk_bf16_f32 v71, v76, v77
	v_cvt_pk_bf16_f32 v72, v78, v79
	v_cvt_pk_bf16_f32 v73, v80, v81
	s_waitcnt lgkmcnt(6)
	v_mfma_f32_32x32x16_bf16 v[2:17], v[248:251], v[232:235], v[2:17]
	ds_read_b64_tr_b16 v[232:233], v96 offset:0x3200
	ds_read_b64_tr_b16 v[234:235], v96 offset:0x3a00
	v_add_f32_e32 v82, v240, v242
	s_nop 0
	v_mov_b32_e32 v83, v82
	v_permlane32_swap_b32_e32 v66, v68
	v_permlane32_swap_b32_e32 v67, v69
	v_permlane32_swap_b32_e32 v70, v72
	v_permlane32_swap_b32_e32 v71, v73
	v_permlane32_swap_b32_e32 v82, v83
	s_waitcnt lgkmcnt(6)
	v_mfma_f32_32x32x16_bf16 v[50:65], v[66:69], v[84:87], v[50:65]
	ds_read_b64_tr_b16 v[84:85], v96 offset:0x2400
	ds_read_b64_tr_b16 v[86:87], v96 offset:0x2c00
	s_waitcnt lgkmcnt(6)
	v_mfma_f32_32x32x16_bf16 v[50:65], v[70:73], v[88:91], v[50:65]
	ds_read_b64_tr_b16 v[88:89], v96 offset:0x3400
	ds_read_b64_tr_b16 v[90:91], v96 offset:0x3c00
	s_waitcnt lgkmcnt(6)
	v_mfma_f32_32x32x16_bf16 v[34:49], v[66:69], v[92:95], v[34:49]
	ds_read_b64_tr_b16 v[92:93], v96 offset:0x2600
	ds_read_b64_tr_b16 v[94:95], v96 offset:0x2e00
	s_waitcnt lgkmcnt(6)
	v_mfma_f32_32x32x16_bf16 v[34:49], v[70:73], v[232:235], v[34:49]
	ds_read_b64_tr_b16 v[232:233], v96 offset:0x3600
	ds_read_b64_tr_b16 v[234:235], v96 offset:0x3e00
	s_waitcnt lgkmcnt(6)
	v_mfma_f32_32x32x16_bf16 v[18:33], v[66:69], v[84:87], v[18:33]
	s_waitcnt lgkmcnt(4)
	v_mfma_f32_32x32x16_bf16 v[18:33], v[70:73], v[88:91], v[18:33]
	s_waitcnt lgkmcnt(2)
	s_andn2_b64 vcc, exec, s[14:15]
	v_mfma_f32_32x32x16_bf16 v[2:17], v[66:69], v[92:95], v[2:17]
	s_waitcnt lgkmcnt(0)
	v_mfma_f32_32x32x16_bf16 v[2:17], v[70:73], v[232:235], v[2:17]
	s_cbranch_vccnz .LBB0_66
	s_xor_b32 s2, s16, 0x4000
	s_add_i32 s3, s2, 0
	v_add_u32_e32 v66, s3, v195
	s_waitcnt vmcnt(4)
	ds_write_b128 v66, v[146:149]
	v_add_u32_e32 v66, s3, v196
	s_waitcnt vmcnt(2)
	ds_write_b128 v66, v[154:157]
	v_add_u32_e32 v66, s3, v197
	ds_write_b128 v66, v[150:153] offset:32768
	v_add_u32_e32 v66, s3, v198
	s_waitcnt vmcnt(1)
	ds_write_b128 v66, v[158:161] offset:32768
	v_add_u32_e32 v66, s2, v199
	s_waitcnt vmcnt(0)
	ds_write_b128 v66, v[162:165]
